# grid barrier: followers at 5 in-layer barriers watch the top-level generation word (sampled before arrival) instead of the per-XCD forwarded word; remaining sites use a monotone compare
# speedup vs baseline: 1.0065x; 1.0018x over previous
; DI void xcd_barrier(const XcdBarrier& b) {
;   asm volatile("s_waitcnt vmcnt(0)" ::: "memory");
;   __syncthreads();
;   if (threadIdx.x == 0) {
;     unsigned* bar = b.bar;
;     __builtin_amdgcn_s_waitcnt(0);
;     unsigned nloc = b.st[0], nx = b.st[1];
;     if (nloc == 0u) { xcd_barrier_complete(bar, b.x, nloc, nx); b.st[0] = nloc; b.st[1] = nx; }
.LBB0_490:
	v_readlane_b32 s100, v253, 25
	v_readlane_b32 s101, v253, 26
	s_nop 4
	global_load_dword v30, v2, s[100:101] sc1
	s_waitcnt vmcnt(0)
	s_waitcnt lgkmcnt(0)
	s_barrier
	s_mov_b64 s[0:1], exec
	v_readlane_b32 s2, v252, 3
	v_readlane_b32 s3, v252, 4
	s_and_b64 s[2:3], s[0:1], s[2:3]
	s_mov_b64 exec, s[2:3]
	s_cbranch_execz .LBB0_542
	v_mov_b32_e32 v0, 0x21000
	s_waitcnt vmcnt(0) expcnt(0) lgkmcnt(0)
	ds_read_b32 v3, v0
	v_mov_b32_e32 v0, 0x21004
	ds_read_b32 v0, v0
	s_waitcnt lgkmcnt(1)
	v_cmp_ne_u32_e32 vcc, 0, v3
	s_cbranch_vccnz .LBB0_506
	s_mov_b32 s7, 1
	s_branch .LBB0_494

; DI unsigned xb_ld(unsigned* p) { return __hip_atomic_load(p, __ATOMIC_RELAXED, __HIP_MEMORY_SCOPE_AGENT); }
; DI unsigned xb_add(unsigned* p, unsigned v) { return __hip_atomic_fetch_add(p, v, __ATOMIC_RELAXED, __HIP_MEMORY_SCOPE_AGENT); }
; #define XB_SPIN(cond, bar) do { unsigned _sp = 0; while (cond) { __builtin_amdgcn_s_sleep(1); \
;     if ((++_sp & 255u) == 0u) { if (xb_ld(&(bar)[XB_TMO])) break; if (_sp > XB_SPIN_CAP) { atomicAdd(&(bar)[XB_TMO], 1u); break; } } } } while (0)
; DI void xcd_barrier(const XcdBarrier& b) {
;     ...
;     const unsigned old = xb_add(&bar[XB_XSUB(b.x)], 1u);
;     const unsigned gen = old / nloc;
;     if (old + 1u == (gen + 1u) * nloc) {
;       __builtin_amdgcn_fence(__ATOMIC_RELEASE, "agent");
;       asm volatile("s_waitcnt vmcnt(0)" ::: "memory");
;       const unsigned og = xb_add(&bar[XB_TOP], 1u);
;       const unsigned tg = og / nx;
;       if (og + 1u == (tg + 1u) * nx) xb_add(&bar[XB_TOPGEN], 1u);
;       else XB_SPIN(xb_ld(&bar[XB_TOPGEN]) == tg, bar);
;       __builtin_amdgcn_fence(__ATOMIC_ACQUIRE, "agent");
;       xb_add(&bar[XB_XGEN(b.x)], 1u);
;       asm volatile("s_waitcnt vmcnt(0)" ::: "memory");
;     } else {
;       XB_SPIN(xb_ld(&bar[XB_XGEN(b.x)]) == gen, bar);
.LBB0_508:
	s_or_b64 exec, exec, s[2:3]
	v_cvt_f32_u32_e32 v5, v3
	s_waitcnt vmcnt(0)
	v_readfirstlane_b32 s2, v4
	buffer_inv sc1
	v_sub_u32_e32 v4, 0, v3
	v_rcp_iflag_f32_e32 v5, v5
	v_add_u32_e32 v6, s2, v1
	v_mul_f32_e32 v5, 0x4f7ffffe, v5
	v_cvt_u32_f32_e32 v5, v5
	v_mul_lo_u32 v1, v4, v5
	v_mul_hi_u32 v1, v5, v1
	v_add_u32_e32 v1, v5, v1
	v_mul_hi_u32 v1, v6, v1
	v_mul_lo_u32 v4, v1, v3
	v_sub_u32_e32 v4, v6, v4
	v_add_u32_e32 v5, 1, v1
	v_cmp_ge_u32_e32 vcc, v4, v3
	s_nop 1
	v_cndmask_b32_e32 v1, v1, v5, vcc
	v_sub_u32_e32 v5, v4, v3
	v_cndmask_b32_e32 v4, v4, v5, vcc
	v_add_u32_e32 v5, 1, v1
	v_cmp_ge_u32_e32 vcc, v4, v3
	v_add_u32_e32 v4, 1, v6
	s_nop 0
	v_cndmask_b32_e32 v1, v1, v5, vcc
	v_mul_lo_u32 v5, v3, v1
	v_add_u32_e32 v3, v5, v3
	v_cmp_ne_u32_e32 vcc, v4, v3
	s_and_saveexec_b64 s[2:3], vcc
	s_xor_b64 s[2:3], exec, s[2:3]
	s_cbranch_execz .LBB0_522
	v_readlane_b32 s4, v253, 25
	v_readlane_b32 s5, v253, 26
	s_waitcnt lgkmcnt(0)
	s_nop 3
	global_load_dword v0, v2, s[4:5] sc1
	s_waitcnt vmcnt(0)
	v_cmp_eq_u32_e32 vcc, v0, v30
	s_and_saveexec_b64 s[4:5], vcc
	s_cbranch_execz .LBB0_521
	s_mov_b32 s7, 1
	s_mov_b64 s[12:13], 0
	s_branch .LBB0_512

; DI unsigned xb_ld(unsigned* p) { return __hip_atomic_load(p, __ATOMIC_RELAXED, __HIP_MEMORY_SCOPE_AGENT); }
; #define XB_SPIN(cond, bar) do { unsigned _sp = 0; while (cond) { __builtin_amdgcn_s_sleep(1); \
;     if ((++_sp & 255u) == 0u) { if (xb_ld(&(bar)[XB_TMO])) break; if (_sp > XB_SPIN_CAP) { atomicAdd(&(bar)[XB_TMO], 1u); break; } } } } while (0)
; DI void xcd_barrier(const XcdBarrier& b) {
;     ...
;       XB_SPIN(xb_ld(&bar[XB_XGEN(b.x)]) == gen, bar);
.LBB0_516:
	v_readlane_b32 s20, v253, 25
	v_readlane_b32 s21, v253, 26
	s_add_i32 s7, s7, 1
	s_mov_b64 s[24:25], -1
	s_nop 2
	global_load_dword v0, v2, s[20:21] sc1
	s_waitcnt vmcnt(0)
	v_cmp_ne_u32_e32 vcc, v0, v30
	s_orn2_b64 s[20:21], vcc, exec
	s_branch .LBB0_511

; DI void xcd_barrier(const XcdBarrier& b) {
;   asm volatile("s_waitcnt vmcnt(0)" ::: "memory");
;   __syncthreads();
;   if (threadIdx.x == 0) {
;     unsigned* bar = b.bar;
;     __builtin_amdgcn_s_waitcnt(0);
;     unsigned nloc = b.st[0], nx = b.st[1];
;     if (nloc == 0u) { xcd_barrier_complete(bar, b.x, nloc, nx); b.st[0] = nloc; b.st[1] = nx; }
.LBB0_578:
	v_readlane_b32 s100, v253, 25
	v_readlane_b32 s101, v253, 26
	s_nop 4
	global_load_dword v30, v2, s[100:101] sc1
	s_waitcnt vmcnt(0)
	s_barrier
	s_mov_b64 s[0:1], exec
	v_readlane_b32 s2, v252, 3
	v_readlane_b32 s3, v252, 4
	s_and_b64 s[2:3], s[0:1], s[2:3]
	s_mov_b64 exec, s[2:3]
	s_cbranch_execz .LBB0_630
	v_mov_b32_e32 v0, 0x21000
	s_waitcnt vmcnt(0) expcnt(0) lgkmcnt(0)
	ds_read_b32 v3, v0
	v_mov_b32_e32 v0, 0x21004
	ds_read_b32 v0, v0
	s_waitcnt lgkmcnt(1)
	v_cmp_ne_u32_e32 vcc, 0, v3
	s_cbranch_vccnz .LBB0_594
	s_mov_b32 s7, 1
	s_branch .LBB0_582

; DI unsigned xb_ld(unsigned* p) { return __hip_atomic_load(p, __ATOMIC_RELAXED, __HIP_MEMORY_SCOPE_AGENT); }
; DI unsigned xb_add(unsigned* p, unsigned v) { return __hip_atomic_fetch_add(p, v, __ATOMIC_RELAXED, __HIP_MEMORY_SCOPE_AGENT); }
; #define XB_SPIN(cond, bar) do { unsigned _sp = 0; while (cond) { __builtin_amdgcn_s_sleep(1); \
;     if ((++_sp & 255u) == 0u) { if (xb_ld(&(bar)[XB_TMO])) break; if (_sp > XB_SPIN_CAP) { atomicAdd(&(bar)[XB_TMO], 1u); break; } } } } while (0)
; DI void xcd_barrier(const XcdBarrier& b) {
;     ...
;     const unsigned old = xb_add(&bar[XB_XSUB(b.x)], 1u);
;     const unsigned gen = old / nloc;
;     if (old + 1u == (gen + 1u) * nloc) {
;       __builtin_amdgcn_fence(__ATOMIC_RELEASE, "agent");
;       asm volatile("s_waitcnt vmcnt(0)" ::: "memory");
;       const unsigned og = xb_add(&bar[XB_TOP], 1u);
;       const unsigned tg = og / nx;
;       if (og + 1u == (tg + 1u) * nx) xb_add(&bar[XB_TOPGEN], 1u);
;       else XB_SPIN(xb_ld(&bar[XB_TOPGEN]) == tg, bar);
;       __builtin_amdgcn_fence(__ATOMIC_ACQUIRE, "agent");
;       xb_add(&bar[XB_XGEN(b.x)], 1u);
;       asm volatile("s_waitcnt vmcnt(0)" ::: "memory");
;     } else {
;       XB_SPIN(xb_ld(&bar[XB_XGEN(b.x)]) == gen, bar);
.LBB0_596:
	s_or_b64 exec, exec, s[2:3]
	v_cvt_f32_u32_e32 v5, v3
	s_waitcnt vmcnt(0)
	v_readfirstlane_b32 s2, v4
	buffer_inv sc1
	v_sub_u32_e32 v4, 0, v3
	v_rcp_iflag_f32_e32 v5, v5
	v_add_u32_e32 v6, s2, v1
	v_mul_f32_e32 v5, 0x4f7ffffe, v5
	v_cvt_u32_f32_e32 v5, v5
	v_mul_lo_u32 v1, v4, v5
	v_mul_hi_u32 v1, v5, v1
	v_add_u32_e32 v1, v5, v1
	v_mul_hi_u32 v1, v6, v1
	v_mul_lo_u32 v4, v1, v3
	v_sub_u32_e32 v4, v6, v4
	v_add_u32_e32 v5, 1, v1
	v_cmp_ge_u32_e32 vcc, v4, v3
	s_nop 1
	v_cndmask_b32_e32 v1, v1, v5, vcc
	v_sub_u32_e32 v5, v4, v3
	v_cndmask_b32_e32 v4, v4, v5, vcc
	v_add_u32_e32 v5, 1, v1
	v_cmp_ge_u32_e32 vcc, v4, v3
	v_add_u32_e32 v4, 1, v6
	s_nop 0
	v_cndmask_b32_e32 v1, v1, v5, vcc
	v_mul_lo_u32 v5, v3, v1
	v_add_u32_e32 v3, v5, v3
	v_cmp_ne_u32_e32 vcc, v4, v3
	s_and_saveexec_b64 s[2:3], vcc
	s_xor_b64 s[2:3], exec, s[2:3]
	s_cbranch_execz .LBB0_610
	v_readlane_b32 s4, v253, 25
	v_readlane_b32 s5, v253, 26
	s_waitcnt lgkmcnt(0)
	s_nop 3
	global_load_dword v0, v2, s[4:5] sc1
	s_waitcnt vmcnt(0)
	v_cmp_eq_u32_e32 vcc, v0, v30
	s_and_saveexec_b64 s[4:5], vcc
	s_cbranch_execz .LBB0_609
	s_mov_b32 s7, 1
	s_mov_b64 s[8:9], 0
	s_branch .LBB0_600

; DI unsigned xb_ld(unsigned* p) { return __hip_atomic_load(p, __ATOMIC_RELAXED, __HIP_MEMORY_SCOPE_AGENT); }
; #define XB_SPIN(cond, bar) do { unsigned _sp = 0; while (cond) { __builtin_amdgcn_s_sleep(1); \
;     if ((++_sp & 255u) == 0u) { if (xb_ld(&(bar)[XB_TMO])) break; if (_sp > XB_SPIN_CAP) { atomicAdd(&(bar)[XB_TMO], 1u); break; } } } } while (0)
; DI void xcd_barrier(const XcdBarrier& b) {
;     ...
;       XB_SPIN(xb_ld(&bar[XB_XGEN(b.x)]) == gen, bar);
.LBB0_604:
	v_readlane_b32 s14, v253, 25
	v_readlane_b32 s15, v253, 26
	s_add_i32 s7, s7, 1
	s_mov_b64 s[20:21], -1
	s_nop 2
	global_load_dword v0, v2, s[14:15] sc1
	s_waitcnt vmcnt(0)
	v_cmp_ne_u32_e32 vcc, v0, v30
	s_orn2_b64 s[14:15], vcc, exec
	s_branch .LBB0_599

; DI void xcd_barrier(const XcdBarrier& b) {
;   asm volatile("s_waitcnt vmcnt(0)" ::: "memory");
;   __syncthreads();
;   if (threadIdx.x == 0) {
;     unsigned* bar = b.bar;
;     __builtin_amdgcn_s_waitcnt(0);
;     unsigned nloc = b.st[0], nx = b.st[1];
;     if (nloc == 0u) { xcd_barrier_complete(bar, b.x, nloc, nx); b.st[0] = nloc; b.st[1] = nx; }
.LBB0_850:
	s_setprio 0
	v_readlane_b32 s100, v253, 25
	v_readlane_b32 s101, v253, 26
	s_nop 4
	global_load_dword v30, v2, s[100:101] sc1
	s_waitcnt vmcnt(0)
	s_barrier
	s_mov_b64 s[0:1], exec
	v_readlane_b32 s2, v252, 3
	v_readlane_b32 s3, v252, 4
	s_and_b64 s[2:3], s[0:1], s[2:3]
	s_mov_b64 exec, s[2:3]
	s_cbranch_execz .LBB0_902
	v_mov_b32_e32 v0, 0x21000
	s_waitcnt vmcnt(0) expcnt(0) lgkmcnt(0)
	ds_read_b32 v3, v0
	v_mov_b32_e32 v0, 0x21004
	ds_read_b32 v0, v0
	s_waitcnt lgkmcnt(1)
	v_cmp_ne_u32_e32 vcc, 0, v3
	s_cbranch_vccnz .LBB0_866
	s_mov_b32 s8, 1
	s_branch .LBB0_854

; DI unsigned xb_ld(unsigned* p) { return __hip_atomic_load(p, __ATOMIC_RELAXED, __HIP_MEMORY_SCOPE_AGENT); }
; DI unsigned xb_add(unsigned* p, unsigned v) { return __hip_atomic_fetch_add(p, v, __ATOMIC_RELAXED, __HIP_MEMORY_SCOPE_AGENT); }
; #define XB_SPIN(cond, bar) do { unsigned _sp = 0; while (cond) { __builtin_amdgcn_s_sleep(1); \
;     if ((++_sp & 255u) == 0u) { if (xb_ld(&(bar)[XB_TMO])) break; if (_sp > XB_SPIN_CAP) { atomicAdd(&(bar)[XB_TMO], 1u); break; } } } } while (0)
; DI void xcd_barrier(const XcdBarrier& b) {
;     ...
;     const unsigned old = xb_add(&bar[XB_XSUB(b.x)], 1u);
;     const unsigned gen = old / nloc;
;     if (old + 1u == (gen + 1u) * nloc) {
;       __builtin_amdgcn_fence(__ATOMIC_RELEASE, "agent");
;       asm volatile("s_waitcnt vmcnt(0)" ::: "memory");
;       const unsigned og = xb_add(&bar[XB_TOP], 1u);
;       const unsigned tg = og / nx;
;       if (og + 1u == (tg + 1u) * nx) xb_add(&bar[XB_TOPGEN], 1u);
;       else XB_SPIN(xb_ld(&bar[XB_TOPGEN]) == tg, bar);
;       __builtin_amdgcn_fence(__ATOMIC_ACQUIRE, "agent");
;       xb_add(&bar[XB_XGEN(b.x)], 1u);
;       asm volatile("s_waitcnt vmcnt(0)" ::: "memory");
;     } else {
;       XB_SPIN(xb_ld(&bar[XB_XGEN(b.x)]) == gen, bar);
.LBB0_868:
	s_or_b64 exec, exec, s[2:3]
	v_cvt_f32_u32_e32 v5, v3
	s_waitcnt vmcnt(0)
	v_readfirstlane_b32 s2, v4
	buffer_inv sc1
	v_sub_u32_e32 v4, 0, v3
	v_rcp_iflag_f32_e32 v5, v5
	v_add_u32_e32 v6, s2, v1
	v_mul_f32_e32 v5, 0x4f7ffffe, v5
	v_cvt_u32_f32_e32 v5, v5
	v_mul_lo_u32 v1, v4, v5
	v_mul_hi_u32 v1, v5, v1
	v_add_u32_e32 v1, v5, v1
	v_mul_hi_u32 v1, v6, v1
	v_mul_lo_u32 v4, v1, v3
	v_sub_u32_e32 v4, v6, v4
	v_add_u32_e32 v5, 1, v1
	v_cmp_ge_u32_e32 vcc, v4, v3
	s_nop 1
	v_cndmask_b32_e32 v1, v1, v5, vcc
	v_sub_u32_e32 v5, v4, v3
	v_cndmask_b32_e32 v4, v4, v5, vcc
	v_add_u32_e32 v5, 1, v1
	v_cmp_ge_u32_e32 vcc, v4, v3
	v_add_u32_e32 v4, 1, v6
	s_nop 0
	v_cndmask_b32_e32 v1, v1, v5, vcc
	v_mul_lo_u32 v5, v3, v1
	v_add_u32_e32 v3, v5, v3
	v_cmp_ne_u32_e32 vcc, v4, v3
	s_and_saveexec_b64 s[2:3], vcc
	s_xor_b64 s[2:3], exec, s[2:3]
	s_cbranch_execz .LBB0_882
	v_readlane_b32 s4, v253, 25
	v_readlane_b32 s5, v253, 26
	s_waitcnt lgkmcnt(0)
	s_nop 3
	global_load_dword v0, v2, s[4:5] sc1
	s_waitcnt vmcnt(0)
	v_cmp_eq_u32_e32 vcc, v0, v30
	s_and_saveexec_b64 s[4:5], vcc
	s_cbranch_execz .LBB0_881
	s_mov_b32 s24, 1
	s_mov_b64 s[6:7], 0
	s_branch .LBB0_872

; DI unsigned xb_ld(unsigned* p) { return __hip_atomic_load(p, __ATOMIC_RELAXED, __HIP_MEMORY_SCOPE_AGENT); }
; #define XB_SPIN(cond, bar) do { unsigned _sp = 0; while (cond) { __builtin_amdgcn_s_sleep(1); \
;     if ((++_sp & 255u) == 0u) { if (xb_ld(&(bar)[XB_TMO])) break; if (_sp > XB_SPIN_CAP) { atomicAdd(&(bar)[XB_TMO], 1u); break; } } } } while (0)
; DI void xcd_barrier(const XcdBarrier& b) {
;     ...
;       XB_SPIN(xb_ld(&bar[XB_XGEN(b.x)]) == gen, bar);
.LBB0_876:
	v_readlane_b32 s12, v253, 25
	v_readlane_b32 s13, v253, 26
	s_add_i32 s24, s24, 1
	s_mov_b64 s[14:15], -1
	s_nop 2
	global_load_dword v0, v2, s[12:13] sc1
	s_waitcnt vmcnt(0)
	v_cmp_ne_u32_e32 vcc, v0, v30
	s_orn2_b64 s[12:13], vcc, exec
	s_branch .LBB0_871

; DI unsigned xb_ld(unsigned* p) { return __hip_atomic_load(p, __ATOMIC_RELAXED, __HIP_MEMORY_SCOPE_AGENT); }
; DI unsigned xb_add(unsigned* p, unsigned v) { return __hip_atomic_fetch_add(p, v, __ATOMIC_RELAXED, __HIP_MEMORY_SCOPE_AGENT); }
; #define XB_SPIN(cond, bar) do { unsigned _sp = 0; while (cond) { __builtin_amdgcn_s_sleep(1); \
;     if ((++_sp & 255u) == 0u) { if (xb_ld(&(bar)[XB_TMO])) break; if (_sp > XB_SPIN_CAP) { atomicAdd(&(bar)[XB_TMO], 1u); break; } } } } while (0)
; DI void xcd_barrier(const XcdBarrier& b) {
;     ...
;     const unsigned old = xb_add(&bar[XB_XSUB(b.x)], 1u);
;     const unsigned gen = old / nloc;
;     if (old + 1u == (gen + 1u) * nloc) {
;       __builtin_amdgcn_fence(__ATOMIC_RELEASE, "agent");
;       asm volatile("s_waitcnt vmcnt(0)" ::: "memory");
;       const unsigned og = xb_add(&bar[XB_TOP], 1u);
;       const unsigned tg = og / nx;
;       if (og + 1u == (tg + 1u) * nx) xb_add(&bar[XB_TOPGEN], 1u);
;       else XB_SPIN(xb_ld(&bar[XB_TOPGEN]) == tg, bar);
;       __builtin_amdgcn_fence(__ATOMIC_ACQUIRE, "agent");
;       xb_add(&bar[XB_XGEN(b.x)], 1u);
;       asm volatile("s_waitcnt vmcnt(0)" ::: "memory");
;     } else {
;       XB_SPIN(xb_ld(&bar[XB_XGEN(b.x)]) == gen, bar);
.LBB0_963:
	s_or_b64 exec, exec, s[2:3]
	v_cvt_f32_u32_e32 v5, v3
	s_waitcnt vmcnt(0)
	v_readfirstlane_b32 s2, v4
	buffer_inv sc1
	v_sub_u32_e32 v4, 0, v3
	v_rcp_iflag_f32_e32 v5, v5
	v_add_u32_e32 v6, s2, v1
	v_mul_f32_e32 v5, 0x4f7ffffe, v5
	v_cvt_u32_f32_e32 v5, v5
	v_mul_lo_u32 v1, v4, v5
	v_mul_hi_u32 v1, v5, v1
	v_add_u32_e32 v1, v5, v1
	v_mul_hi_u32 v1, v6, v1
	v_mul_lo_u32 v4, v1, v3
	v_sub_u32_e32 v4, v6, v4
	v_add_u32_e32 v5, 1, v1
	v_cmp_ge_u32_e32 vcc, v4, v3
	s_nop 1
	v_cndmask_b32_e32 v1, v1, v5, vcc
	v_sub_u32_e32 v5, v4, v3
	v_cndmask_b32_e32 v4, v4, v5, vcc
	v_add_u32_e32 v5, 1, v1
	v_cmp_ge_u32_e32 vcc, v4, v3
	v_add_u32_e32 v4, 1, v6
	s_nop 0
	v_cndmask_b32_e32 v1, v1, v5, vcc
	v_mul_lo_u32 v5, v3, v1
	v_add_u32_e32 v3, v5, v3
	v_cmp_ne_u32_e32 vcc, v4, v3
	s_and_saveexec_b64 s[2:3], vcc
	s_xor_b64 s[2:3], exec, s[2:3]
	s_cbranch_execz .LBB0_977
	v_readlane_b32 s4, v253, 21
	v_readlane_b32 s5, v253, 22
	s_waitcnt lgkmcnt(0)
	s_nop 3
	global_load_dword v0, v2, s[4:5] sc1
	s_waitcnt vmcnt(0)
	v_cmp_ge_u32_e32 vcc, v1, v0
	s_and_saveexec_b64 s[4:5], vcc
	s_cbranch_execz .LBB0_976
	s_mov_b32 s24, 1
	s_mov_b64 s[6:7], 0
	s_branch .LBB0_967

; DI unsigned xb_ld(unsigned* p) { return __hip_atomic_load(p, __ATOMIC_RELAXED, __HIP_MEMORY_SCOPE_AGENT); }
; #define XB_SPIN(cond, bar) do { unsigned _sp = 0; while (cond) { __builtin_amdgcn_s_sleep(1); \
;     if ((++_sp & 255u) == 0u) { if (xb_ld(&(bar)[XB_TMO])) break; if (_sp > XB_SPIN_CAP) { atomicAdd(&(bar)[XB_TMO], 1u); break; } } } } while (0)
; DI void xcd_barrier(const XcdBarrier& b) {
;     ...
;       XB_SPIN(xb_ld(&bar[XB_XGEN(b.x)]) == gen, bar);
.LBB0_971:
	v_readlane_b32 s12, v253, 21
	v_readlane_b32 s13, v253, 22
	s_add_i32 s24, s24, 1
	s_mov_b64 s[14:15], -1
	s_nop 2
	global_load_dword v0, v2, s[12:13] sc1
	s_waitcnt vmcnt(0)
	v_cmp_lt_u32_e32 vcc, v1, v0
	s_orn2_b64 s[12:13], vcc, exec
	s_branch .LBB0_966

; DI void xcd_barrier(const XcdBarrier& b) {
;   asm volatile("s_waitcnt vmcnt(0)" ::: "memory");
;   __syncthreads();
;   if (threadIdx.x == 0) {
;     unsigned* bar = b.bar;
;     __builtin_amdgcn_s_waitcnt(0);
;     unsigned nloc = b.st[0], nx = b.st[1];
;     if (nloc == 0u) { xcd_barrier_complete(bar, b.x, nloc, nx); b.st[0] = nloc; b.st[1] = nx; }
.LBB0_1020:
	v_readlane_b32 s100, v253, 25
	v_readlane_b32 s101, v253, 26
	s_nop 4
	global_load_dword v30, v2, s[100:101] sc1
	s_waitcnt vmcnt(0)
	s_barrier
	s_mov_b64 s[0:1], exec
	v_readlane_b32 s2, v252, 3
	v_readlane_b32 s3, v252, 4
	s_and_b64 s[2:3], s[0:1], s[2:3]
	s_mov_b64 exec, s[2:3]
	s_cbranch_execz .LBB0_1072
	v_mov_b32_e32 v0, 0x21000
	s_waitcnt vmcnt(0) expcnt(0) lgkmcnt(0)
	ds_read_b32 v3, v0
	v_mov_b32_e32 v0, 0x21004
	ds_read_b32 v0, v0
	s_waitcnt lgkmcnt(1)
	v_cmp_ne_u32_e32 vcc, 0, v3
	s_cbranch_vccnz .LBB0_1036
	s_mov_b32 s8, 1
	s_branch .LBB0_1024
